# GEMM loop: B0 fragment reads moved to the read-free segment (balanced LDS reads), segment-tail scalar ops issued among the MFMAs
# speedup vs baseline: 1.1016x; 1.0126x over previous
; #define PG8_STAGE(bufoff, gbase, voff) do { _Pragma("unroll") for (int _i = 0; _i < 2; ++_i) \
;         __builtin_amdgcn_global_load_lds((const unsigned*)((const char*)(gbase) + (voff)[_i]), (LAS unsigned*)(lds + (bufoff) + ldsw + _i * 8192), 16, 0, 0); } while (0)
; #define PG8_LDA(dst, b, h) do { _Pragma("unroll") for (int m = 0; m < 4; ++m) _Pragma("unroll") for (int k = 0; k < 2; ++k) dst[m][k] = *(const LAS bf16x8*)(lds + PG8_SA(b, h) + aoff + m * 2048 + k * 1024); } while (0)
; #define PG8_LDB(dst, b, h) do { _Pragma("unroll") for (int n = 0; n < 2; ++n) _Pragma("unroll") for (int k = 0; k < 2; ++k) dst[n][k] = *(const LAS bf16x8*)(lds + PG8_SB(b, h) + boff + n * 2048 + k * 1024); } while (0)
; #define PG8_MMA(ai, bj, At, Bt) do { __builtin_amdgcn_s_setprio(1); _Pragma("unroll") for (int m = 0; m < 4; ++m) _Pragma("unroll") for (int n = 0; n < 2; ++n) _Pragma("unroll") for (int k = 0; k < 2; ++k) \
;         acc[ai][bj][m][n] = __builtin_amdgcn_mfma_f32_16x16x32_bf16(Bt[n][k], At[m][k], acc[ai][bj][m][n], 0, 0, 0); __builtin_amdgcn_s_setprio(0); } while (0)
; #define PG8_WAIT_V(n) asm volatile("s_waitcnt vmcnt(" #n ")" ::: "memory")
; #define PG8_WAIT_L(n) asm volatile("s_waitcnt lgkmcnt(" #n ")" ::: "memory")
; #define PG8_BAR __builtin_amdgcn_s_barrier()
; #define PG8_SCHED __builtin_amdgcn_sched_barrier(0)
; template <class Epi>
; __device__ __forceinline__ void gemm_phase(LAS unsigned char* lds, const Gemm g, const StaticOrder& S, const Epi& E) {
;     ...
;     for (;;) {
;         const bool has_next = S.next(ui + 1, nxt);
;         const char* nA = has_next ? (const char*)g.A + (size_t)nxt.pm * tstepA : cA; const char* nB = has_next ? (const char*)g.Bt + (size_t)nxt.pn * tstepB : cB;
;         for (int t = 0; t < nt; t += 2) {
;     ...
;             PG8_LDB(B0, 0, 0); PG8_SCHED; PG8_LDA(At, 0, 0); PG8_STAGE(PG8_SA(1, 1), a1 + hstepA, voffA);
;             PG8_WAIT_L(8); PG8_BAR; PG8_WAIT_L(0); PG8_MMA(0, 0, At, B0); PG8_BAR; PG8_SCHED;
;             PG8_LDB(B1, 0, 1); PG8_STAGE(PG8_SB(0, 0), b2, voffB);
;             PG8_BAR; PG8_WAIT_L(0); PG8_MMA(0, 1, At, B1); PG8_BAR;
;             PG8_LDA(At, 0, 1); PG8_STAGE(PG8_SA(0, 0), a2, voffA);
;             PG8_BAR; PG8_WAIT_L(0); PG8_MMA(1, 0, At, B0); PG8_BAR; PG8_SCHED;
;             PG8_STAGE(PG8_SB(0, 1), b2 + hstepB, voffB);
;             PG8_WAIT_V(6); PG8_BAR; PG8_MMA(1, 1, At, B1); PG8_BAR;
.Lresync_y:
	v_add_u32_e32 v142, 0x10000, v225
	ds_read_b128 v[130:133], v142
	ds_read_b128 v[134:137], v142 offset:1024
	ds_read_b128 v[138:141], v142 offset:2048
	ds_read_b128 v[142:145], v142 offset:3072
	s_branch .LBB0_117
.LBB0_116:
	s_add_i32 s35, s44, 2
	s_add_u32 s46, s36, 0x80
	s_addc_u32 s45, s37, 0
	s_cmp_eq_u32 s17, s44
	s_cselect_b32 s45, s29, s45
	s_cselect_b32 s44, s28, s46
	s_cselect_b32 s47, s31, s70
	s_cselect_b32 s46, s30, s69
	s_add_i32 s71, 0, 0x10000
	v_lshl_add_u64 v[166:167], s[36:37], 0, v[186:187]
	s_add_i32 m0, s39, 0xc000
	ds_read_b128 v[146:149], v228
	ds_read_b128 v[150:153], v228 offset:1024
	ds_read_b128 v[154:157], v228 offset:2048
	ds_read_b128 v[158:161], v228 offset:3072
	ds_read_b128 v[162:165], v228 offset:4096
	ds_read_b128 v[190:193], v228 offset:5120
	ds_read_b128 v[194:197], v228 offset:6144
	ds_read_b128 v[198:201], v228 offset:7168
	global_load_lds_dwordx4 v[166:167], off
	v_lshl_add_u64 v[166:167], s[36:37], 0, v[188:189]
	s_add_i32 m0, s39, 0xe000
	s_nop 0
	global_load_lds_dwordx4 v[166:167], off
	s_waitcnt lgkmcnt(8)
	s_barrier
	s_waitcnt lgkmcnt(0)
	s_waitcnt lgkmcnt(0)
	v_mfma_f32_16x16x32_bf16 v[124:127], v[130:133], v[146:149], v[124:127]
	v_mfma_f32_16x16x32_bf16 v[120:123], v[138:141], v[146:149], v[120:123]
	v_mfma_f32_16x16x32_bf16 v[112:115], v[130:133], v[154:157], v[112:115]
	v_mfma_f32_16x16x32_bf16 v[104:107], v[138:141], v[154:157], v[104:107]
	v_mfma_f32_16x16x32_bf16 v[96:99], v[130:133], v[162:165], v[96:99]
	v_mfma_f32_16x16x32_bf16 v[88:91], v[138:141], v[162:165], v[88:91]
	v_mfma_f32_16x16x32_bf16 v[80:83], v[130:133], v[194:197], v[80:83]
	v_mfma_f32_16x16x32_bf16 v[72:75], v[138:141], v[194:197], v[72:75]
	v_mfma_f32_16x16x32_bf16 v[124:127], v[134:137], v[150:153], v[124:127]
	v_mfma_f32_16x16x32_bf16 v[120:123], v[142:145], v[150:153], v[120:123]
	v_mfma_f32_16x16x32_bf16 v[112:115], v[134:137], v[158:161], v[112:115]
	v_mfma_f32_16x16x32_bf16 v[104:107], v[142:145], v[158:161], v[104:107]
	v_mfma_f32_16x16x32_bf16 v[96:99], v[134:137], v[190:193], v[96:99]
	v_mfma_f32_16x16x32_bf16 v[88:91], v[142:145], v[190:193], v[88:91]
	v_mfma_f32_16x16x32_bf16 v[80:83], v[134:137], v[198:201], v[80:83]
	v_mfma_f32_16x16x32_bf16 v[72:75], v[142:145], v[198:201], v[72:75]
	s_barrier
	s_add_i32 s72, 0, 0x14000
	v_add_u32_e32 v166, s72, v225
	s_add_i32 s71, s71, s57
	ds_read_b128 v[202:205], v166
	ds_read_b128 v[230:233], v166 offset:1024
	ds_read_b128 v[234:237], v166 offset:2048
	ds_read_b128 v[238:241], v166 offset:3072
	v_lshl_add_u64 v[166:167], s[46:47], 0, v[168:169]
	s_mov_b32 m0, s71
	v_lshl_add_u64 v[206:207], s[46:47], 0, v[178:179]
	global_load_lds_dwordx4 v[166:167], off
	s_add_i32 m0, s71, 0x2000
	s_nop 0
	global_load_lds_dwordx4 v[206:207], off
	s_barrier
	s_waitcnt lgkmcnt(0)
	s_waitcnt lgkmcnt(0)
	v_mfma_f32_16x16x32_bf16 v[116:119], v[202:205], v[146:149], v[116:119]
	v_mfma_f32_16x16x32_bf16 v[108:111], v[234:237], v[146:149], v[108:111]
	v_mfma_f32_16x16x32_bf16 v[100:103], v[202:205], v[154:157], v[100:103]
	v_mfma_f32_16x16x32_bf16 v[92:95], v[234:237], v[154:157], v[92:95]
	s_mov_b32 m0, s39
	v_lshl_add_u64 v[242:243], s[44:45], 0, v[174:175]
	v_mfma_f32_16x16x32_bf16 v[84:87], v[202:205], v[162:165], v[84:87]
	v_mfma_f32_16x16x32_bf16 v[76:79], v[234:237], v[162:165], v[76:79]
	v_mfma_f32_16x16x32_bf16 v[68:71], v[202:205], v[194:197], v[68:71]
	v_mfma_f32_16x16x32_bf16 v[64:67], v[234:237], v[194:197], v[64:67]
	v_mfma_f32_16x16x32_bf16 v[116:119], v[230:233], v[150:153], v[116:119]
	v_mfma_f32_16x16x32_bf16 v[108:111], v[238:241], v[150:153], v[108:111]
	v_mfma_f32_16x16x32_bf16 v[100:103], v[230:233], v[158:161], v[100:103]
	v_mfma_f32_16x16x32_bf16 v[92:95], v[238:241], v[158:161], v[92:95]
	v_mfma_f32_16x16x32_bf16 v[84:87], v[230:233], v[190:193], v[84:87]
	v_mfma_f32_16x16x32_bf16 v[76:79], v[238:241], v[190:193], v[76:79]
	v_mfma_f32_16x16x32_bf16 v[68:71], v[230:233], v[198:201], v[68:71]
	v_mfma_f32_16x16x32_bf16 v[64:67], v[238:241], v[198:201], v[64:67]
	s_barrier
	ds_read_b128 v[146:149], v228 offset:16384
	ds_read_b128 v[150:153], v228 offset:17408
	ds_read_b128 v[154:157], v228 offset:18432
	ds_read_b128 v[158:161], v228 offset:19456
	ds_read_b128 v[162:165], v228 offset:20480
	ds_read_b128 v[190:193], v228 offset:21504
	ds_read_b128 v[194:197], v228 offset:22528
	ds_read_b128 v[198:201], v228 offset:23552
	global_load_lds_dwordx4 v[242:243], off
	v_lshl_add_u64 v[244:245], s[44:45], 0, v[176:177]
	s_mov_b32 m0, s54
	s_nop 0
	global_load_lds_dwordx4 v[244:245], off
	s_waitcnt vmcnt(10)
	s_barrier
	s_waitcnt lgkmcnt(0)
	s_waitcnt lgkmcnt(0)
	v_mfma_f32_16x16x32_bf16 v[60:63], v[130:133], v[146:149], v[60:63]
	v_mfma_f32_16x16x32_bf16 v[56:59], v[138:141], v[146:149], v[56:59]
	v_mfma_f32_16x16x32_bf16 v[52:55], v[130:133], v[154:157], v[52:55]
	v_mfma_f32_16x16x32_bf16 v[44:47], v[138:141], v[154:157], v[44:47]
	v_mfma_f32_16x16x32_bf16 v[36:39], v[130:133], v[162:165], v[36:39]
	v_mfma_f32_16x16x32_bf16 v[28:31], v[138:141], v[162:165], v[28:31]
	v_mfma_f32_16x16x32_bf16 v[20:23], v[130:133], v[194:197], v[20:23]
	v_mfma_f32_16x16x32_bf16 v[12:15], v[138:141], v[194:197], v[12:15]
	v_mfma_f32_16x16x32_bf16 v[60:63], v[134:137], v[150:153], v[60:63]
	v_mfma_f32_16x16x32_bf16 v[56:59], v[142:145], v[150:153], v[56:59]
	v_mfma_f32_16x16x32_bf16 v[52:55], v[134:137], v[158:161], v[52:55]
	v_mfma_f32_16x16x32_bf16 v[44:47], v[142:145], v[158:161], v[44:47]
	v_mfma_f32_16x16x32_bf16 v[36:39], v[134:137], v[190:193], v[36:39]
	v_mfma_f32_16x16x32_bf16 v[28:31], v[142:145], v[190:193], v[28:31]
	v_mfma_f32_16x16x32_bf16 v[20:23], v[134:137], v[198:201], v[20:23]
	v_mfma_f32_16x16x32_bf16 v[12:15], v[142:145], v[198:201], v[12:15]
	s_barrier
; #define PG8_STAGE(bufoff, gbase, voff) do { _Pragma("unroll") for (int _i = 0; _i < 2; ++_i) \
;         __builtin_amdgcn_global_load_lds((const unsigned*)((const char*)(gbase) + (voff)[_i]), (LAS unsigned*)(lds + (bufoff) + ldsw + _i * 8192), 16, 0, 0); } while (0)
; #define PG8_LDA(dst, b, h) do { _Pragma("unroll") for (int m = 0; m < 4; ++m) _Pragma("unroll") for (int k = 0; k < 2; ++k) dst[m][k] = *(const LAS bf16x8*)(lds + PG8_SA(b, h) + aoff + m * 2048 + k * 1024); } while (0)
; #define PG8_LDB(dst, b, h) do { _Pragma("unroll") for (int n = 0; n < 2; ++n) _Pragma("unroll") for (int k = 0; k < 2; ++k) dst[n][k] = *(const LAS bf16x8*)(lds + PG8_SB(b, h) + boff + n * 2048 + k * 1024); } while (0)
; #define PG8_MMA(ai, bj, At, Bt) do { __builtin_amdgcn_s_setprio(1); _Pragma("unroll") for (int m = 0; m < 4; ++m) _Pragma("unroll") for (int n = 0; n < 2; ++n) _Pragma("unroll") for (int k = 0; k < 2; ++k) \
;         acc[ai][bj][m][n] = __builtin_amdgcn_mfma_f32_16x16x32_bf16(Bt[n][k], At[m][k], acc[ai][bj][m][n], 0, 0, 0); __builtin_amdgcn_s_setprio(0); } while (0)
; #define PG8_WAIT_V(n) asm volatile("s_waitcnt vmcnt(" #n ")" ::: "memory")
; #define PG8_WAIT_L(n) asm volatile("s_waitcnt lgkmcnt(" #n ")" ::: "memory")
; #define PG8_BAR __builtin_amdgcn_s_barrier()
; #define PG8_SCHED __builtin_amdgcn_sched_barrier(0)
; template <class Epi>
; __device__ __forceinline__ void gemm_phase(LAS unsigned char* lds, const Gemm g, const StaticOrder& S, const Epi& E) {
;     ...
;             PG8_STAGE(PG8_SB(0, 1), b2 + hstepB, voffB);
;             PG8_WAIT_V(6); PG8_BAR; PG8_MMA(1, 1, At, B1); PG8_BAR;
;             PG8_LDB(B0, 1, 0); PG8_SCHED; PG8_LDA(At, 1, 0); PG8_STAGE(PG8_SA(0, 1), a2 + hstepA, voffA);
;             PG8_WAIT_L(8); PG8_BAR; PG8_WAIT_L(0); PG8_MMA(0, 0, At, B0); PG8_BAR; PG8_SCHED;
;             PG8_LDB(B1, 1, 1); PG8_STAGE(PG8_SB(1, 0), b3, voffB);
	s_add_u32 s46, s46, s50
	s_addc_u32 s47, s47, 0
	s_add_i32 s71, s72, s57
	v_lshl_add_u64 v[246:247], s[46:47], 0, v[168:169]
	s_mov_b32 m0, s71
	v_lshl_add_u64 v[248:249], s[46:47], 0, v[178:179]
	global_load_lds_dwordx4 v[246:247], off
	s_add_i32 m0, s71, 0x2000
	s_nop 0
	global_load_lds_dwordx4 v[248:249], off
	v_add_u32_e32 v142, 0x18000, v225
	ds_read_b128 v[130:133], v142
	ds_read_b128 v[134:137], v142 offset:1024
	ds_read_b128 v[138:141], v142 offset:2048
	ds_read_b128 v[142:145], v142 offset:3072
	s_waitcnt vmcnt(6)
	s_barrier
	v_mfma_f32_16x16x32_bf16 v[48:51], v[202:205], v[146:149], v[48:51]
	v_mfma_f32_16x16x32_bf16 v[40:43], v[234:237], v[146:149], v[40:43]
	v_mfma_f32_16x16x32_bf16 v[32:35], v[202:205], v[154:157], v[32:35]
	v_mfma_f32_16x16x32_bf16 v[24:27], v[234:237], v[154:157], v[24:27]
	s_add_i32 s46, 0, 0x18000
	v_mfma_f32_16x16x32_bf16 v[16:19], v[202:205], v[162:165], v[16:19]
	v_mfma_f32_16x16x32_bf16 v[8:11], v[234:237], v[162:165], v[8:11]
	v_mfma_f32_16x16x32_bf16 v[4:7], v[202:205], v[194:197], v[4:7]
	v_mfma_f32_16x16x32_bf16 v[0:3], v[234:237], v[194:197], v[0:3]
	v_mfma_f32_16x16x32_bf16 v[48:51], v[230:233], v[150:153], v[48:51]
	v_mfma_f32_16x16x32_bf16 v[40:43], v[238:241], v[150:153], v[40:43]
	v_mfma_f32_16x16x32_bf16 v[32:35], v[230:233], v[158:161], v[32:35]
	v_mfma_f32_16x16x32_bf16 v[24:27], v[238:241], v[158:161], v[24:27]
	v_mfma_f32_16x16x32_bf16 v[16:19], v[230:233], v[190:193], v[16:19]
	v_mfma_f32_16x16x32_bf16 v[8:11], v[238:241], v[190:193], v[8:11]
	v_mfma_f32_16x16x32_bf16 v[4:7], v[230:233], v[198:201], v[4:7]
	v_mfma_f32_16x16x32_bf16 v[0:3], v[238:241], v[198:201], v[0:3]
	s_barrier
	s_add_u32 s44, s44, s74
	s_addc_u32 s45, s45, 0
	s_mov_b32 m0, s55
	v_lshl_add_u64 v[202:203], s[44:45], 0, v[174:175]
	ds_read_b128 v[146:149], v228 offset:32768
	ds_read_b128 v[150:153], v228 offset:33792
	ds_read_b128 v[154:157], v228 offset:34816
	ds_read_b128 v[158:161], v228 offset:35840
	ds_read_b128 v[162:165], v228 offset:36864
	ds_read_b128 v[190:193], v228 offset:37888
	ds_read_b128 v[194:197], v228 offset:38912
	ds_read_b128 v[198:201], v228 offset:39936
	global_load_lds_dwordx4 v[202:203], off
	v_lshl_add_u64 v[202:203], s[44:45], 0, v[176:177]
	s_mov_b32 m0, s3
	s_nop 0
	global_load_lds_dwordx4 v[202:203], off
	s_waitcnt lgkmcnt(8)
	s_barrier
	s_waitcnt lgkmcnt(0)
	s_waitcnt lgkmcnt(0)
	v_mfma_f32_16x16x32_bf16 v[124:127], v[130:133], v[146:149], v[124:127]
	v_mfma_f32_16x16x32_bf16 v[120:123], v[138:141], v[146:149], v[120:123]
	v_mfma_f32_16x16x32_bf16 v[112:115], v[130:133], v[154:157], v[112:115]
	v_mfma_f32_16x16x32_bf16 v[104:107], v[138:141], v[154:157], v[104:107]
	v_mfma_f32_16x16x32_bf16 v[96:99], v[130:133], v[162:165], v[96:99]
	v_mfma_f32_16x16x32_bf16 v[88:91], v[138:141], v[162:165], v[88:91]
	v_mfma_f32_16x16x32_bf16 v[80:83], v[130:133], v[194:197], v[80:83]
	v_mfma_f32_16x16x32_bf16 v[72:75], v[138:141], v[194:197], v[72:75]
	v_mfma_f32_16x16x32_bf16 v[124:127], v[134:137], v[150:153], v[124:127]
	v_mfma_f32_16x16x32_bf16 v[120:123], v[142:145], v[150:153], v[120:123]
	v_mfma_f32_16x16x32_bf16 v[112:115], v[134:137], v[158:161], v[112:115]
	v_mfma_f32_16x16x32_bf16 v[104:107], v[142:145], v[158:161], v[104:107]
	v_mfma_f32_16x16x32_bf16 v[96:99], v[134:137], v[190:193], v[96:99]
	v_mfma_f32_16x16x32_bf16 v[88:91], v[142:145], v[190:193], v[88:91]
	v_mfma_f32_16x16x32_bf16 v[80:83], v[134:137], v[198:201], v[80:83]
	v_mfma_f32_16x16x32_bf16 v[72:75], v[142:145], v[198:201], v[72:75]
	s_barrier
	s_add_i32 s44, s46, s57
	v_add_u32_e32 v172, s78, v225
	v_lshl_add_u64 v[166:167], v[166:167], 0, s[88:89]
	s_mov_b32 m0, s44
	ds_read_b128 v[202:205], v172
	ds_read_b128 v[230:233], v172 offset:1024
	ds_read_b128 v[234:237], v172 offset:2048
	ds_read_b128 v[238:241], v172 offset:3072
	global_load_lds_dwordx4 v[166:167], off
	v_lshl_add_u64 v[166:167], v[206:207], 0, s[88:89]
	s_add_i32 m0, s44, 0x2000
	s_nop 0
	global_load_lds_dwordx4 v[166:167], off
	s_barrier
; #define PG8_STAGE(bufoff, gbase, voff) do { _Pragma("unroll") for (int _i = 0; _i < 2; ++_i) \
;         __builtin_amdgcn_global_load_lds((const unsigned*)((const char*)(gbase) + (voff)[_i]), (LAS unsigned*)(lds + (bufoff) + ldsw + _i * 8192), 16, 0, 0); } while (0)
; #define PG8_LDA(dst, b, h) do { _Pragma("unroll") for (int m = 0; m < 4; ++m) _Pragma("unroll") for (int k = 0; k < 2; ++k) dst[m][k] = *(const LAS bf16x8*)(lds + PG8_SA(b, h) + aoff + m * 2048 + k * 1024); } while (0)
; #define PG8_MMA(ai, bj, At, Bt) do { __builtin_amdgcn_s_setprio(1); _Pragma("unroll") for (int m = 0; m < 4; ++m) _Pragma("unroll") for (int n = 0; n < 2; ++n) _Pragma("unroll") for (int k = 0; k < 2; ++k) \
;         acc[ai][bj][m][n] = __builtin_amdgcn_mfma_f32_16x16x32_bf16(Bt[n][k], At[m][k], acc[ai][bj][m][n], 0, 0, 0); __builtin_amdgcn_s_setprio(0); } while (0)
; #define PG8_WAIT_V(n) asm volatile("s_waitcnt vmcnt(" #n ")" ::: "memory")
; #define PG8_WAIT_L(n) asm volatile("s_waitcnt lgkmcnt(" #n ")" ::: "memory")
; #define PG8_BAR __builtin_amdgcn_s_barrier()
; #define PG8_SCHED __builtin_amdgcn_sched_barrier(0)
; template <class Epi>
; __device__ __forceinline__ void gemm_phase(LAS unsigned char* lds, const Gemm g, const StaticOrder& S, const Epi& E) {
;     ...
;             PG8_BAR; PG8_WAIT_L(0); PG8_MMA(0, 1, At, B1); PG8_BAR;
;             PG8_LDA(At, 1, 1); PG8_STAGE(PG8_SA(1, 0), a3, voffA);
;             PG8_BAR; PG8_WAIT_L(0); PG8_MMA(1, 0, At, B0); PG8_BAR; PG8_SCHED;
;             PG8_STAGE(PG8_SB(1, 1), b3 + hstepB, voffB);
;             PG8_WAIT_V(6); PG8_BAR; PG8_MMA(1, 1, At, B1); PG8_BAR;
;         }
	s_waitcnt lgkmcnt(0)
	s_waitcnt lgkmcnt(0)
	v_mfma_f32_16x16x32_bf16 v[116:119], v[202:205], v[146:149], v[116:119]
	v_mfma_f32_16x16x32_bf16 v[108:111], v[234:237], v[146:149], v[108:111]
	v_mfma_f32_16x16x32_bf16 v[100:103], v[202:205], v[154:157], v[100:103]
	v_mfma_f32_16x16x32_bf16 v[92:95], v[234:237], v[154:157], v[92:95]
	s_mov_b32 m0, s60
	v_lshl_add_u64 v[166:167], v[242:243], 0, s[88:89]
	v_mfma_f32_16x16x32_bf16 v[84:87], v[202:205], v[162:165], v[84:87]
	v_mfma_f32_16x16x32_bf16 v[76:79], v[234:237], v[162:165], v[76:79]
	v_mfma_f32_16x16x32_bf16 v[68:71], v[202:205], v[194:197], v[68:71]
	v_mfma_f32_16x16x32_bf16 v[64:67], v[234:237], v[194:197], v[64:67]
	v_mfma_f32_16x16x32_bf16 v[116:119], v[230:233], v[150:153], v[116:119]
	v_mfma_f32_16x16x32_bf16 v[108:111], v[238:241], v[150:153], v[108:111]
	v_mfma_f32_16x16x32_bf16 v[100:103], v[230:233], v[158:161], v[100:103]
	v_mfma_f32_16x16x32_bf16 v[92:95], v[238:241], v[158:161], v[92:95]
	v_mfma_f32_16x16x32_bf16 v[84:87], v[230:233], v[190:193], v[84:87]
	v_mfma_f32_16x16x32_bf16 v[76:79], v[238:241], v[190:193], v[76:79]
	v_mfma_f32_16x16x32_bf16 v[68:71], v[230:233], v[198:201], v[68:71]
	v_mfma_f32_16x16x32_bf16 v[64:67], v[238:241], v[198:201], v[64:67]
	s_barrier
	ds_read_b128 v[146:149], v228 offset:49152
	ds_read_b128 v[150:153], v228 offset:50176
	ds_read_b128 v[154:157], v228 offset:51200
	ds_read_b128 v[158:161], v228 offset:52224
	ds_read_b128 v[162:165], v228 offset:53248
	ds_read_b128 v[190:193], v228 offset:54272
	ds_read_b128 v[194:197], v228 offset:55296
	ds_read_b128 v[198:201], v228 offset:56320
	global_load_lds_dwordx4 v[166:167], off
	v_lshl_add_u64 v[166:167], v[244:245], 0, s[88:89]
	s_mov_b32 m0, s61
	s_nop 0
	global_load_lds_dwordx4 v[166:167], off
	s_waitcnt vmcnt(10)
	s_barrier
	s_waitcnt lgkmcnt(0)
	s_waitcnt lgkmcnt(0)
	v_mfma_f32_16x16x32_bf16 v[60:63], v[130:133], v[146:149], v[60:63]
	v_mfma_f32_16x16x32_bf16 v[56:59], v[138:141], v[146:149], v[56:59]
	v_mfma_f32_16x16x32_bf16 v[52:55], v[130:133], v[154:157], v[52:55]
	v_mfma_f32_16x16x32_bf16 v[44:47], v[138:141], v[154:157], v[44:47]
	v_mfma_f32_16x16x32_bf16 v[36:39], v[130:133], v[162:165], v[36:39]
	v_mfma_f32_16x16x32_bf16 v[28:31], v[138:141], v[162:165], v[28:31]
	v_mfma_f32_16x16x32_bf16 v[20:23], v[130:133], v[194:197], v[20:23]
	v_mfma_f32_16x16x32_bf16 v[12:15], v[138:141], v[194:197], v[12:15]
	v_mfma_f32_16x16x32_bf16 v[60:63], v[134:137], v[150:153], v[60:63]
	v_mfma_f32_16x16x32_bf16 v[56:59], v[142:145], v[150:153], v[56:59]
	v_mfma_f32_16x16x32_bf16 v[52:55], v[134:137], v[158:161], v[52:55]
	v_mfma_f32_16x16x32_bf16 v[44:47], v[142:145], v[158:161], v[44:47]
	v_mfma_f32_16x16x32_bf16 v[36:39], v[134:137], v[190:193], v[36:39]
	v_mfma_f32_16x16x32_bf16 v[28:31], v[142:145], v[190:193], v[28:31]
	v_mfma_f32_16x16x32_bf16 v[20:23], v[134:137], v[198:201], v[20:23]
	v_mfma_f32_16x16x32_bf16 v[12:15], v[142:145], v[198:201], v[12:15]
	s_barrier
	s_add_i32 s44, s78, s57
	v_lshl_add_u64 v[130:131], v[246:247], 0, s[88:89]
	s_mov_b32 m0, s44
	s_nop 0
	global_load_lds_dwordx4 v[130:131], off
	v_lshl_add_u64 v[130:131], v[248:249], 0, s[88:89]
	s_add_i32 m0, s44, 0x2000
	s_nop 0
	global_load_lds_dwordx4 v[130:131], off
	v_add_u32_e32 v142, 0x10000, v225
	ds_read_b128 v[130:133], v142
	ds_read_b128 v[134:137], v142 offset:1024
	ds_read_b128 v[138:141], v142 offset:2048
	ds_read_b128 v[142:145], v142 offset:3072
	s_waitcnt vmcnt(6)
	s_barrier
	v_mfma_f32_16x16x32_bf16 v[48:51], v[202:205], v[146:149], v[48:51]
	v_mfma_f32_16x16x32_bf16 v[40:43], v[234:237], v[146:149], v[40:43]
	v_mfma_f32_16x16x32_bf16 v[32:35], v[202:205], v[154:157], v[32:35]
	v_mfma_f32_16x16x32_bf16 v[24:27], v[234:237], v[154:157], v[24:27]
	s_add_u32 s36, s36, 0x100
	s_addc_u32 s37, s37, 0
	s_add_u32 s69, s69, 0x100
	s_addc_u32 s70, s70, 0
	s_cmp_ge_u32 s35, s16
	s_mov_b32 s44, s35
	v_mfma_f32_16x16x32_bf16 v[16:19], v[202:205], v[162:165], v[16:19]
	v_mfma_f32_16x16x32_bf16 v[8:11], v[234:237], v[162:165], v[8:11]
	v_mfma_f32_16x16x32_bf16 v[4:7], v[202:205], v[194:197], v[4:7]
	v_mfma_f32_16x16x32_bf16 v[0:3], v[234:237], v[194:197], v[0:3]
	v_mfma_f32_16x16x32_bf16 v[48:51], v[230:233], v[150:153], v[48:51]
	v_mfma_f32_16x16x32_bf16 v[40:43], v[238:241], v[150:153], v[40:43]
	v_mfma_f32_16x16x32_bf16 v[32:35], v[230:233], v[158:161], v[32:35]
	v_mfma_f32_16x16x32_bf16 v[24:27], v[238:241], v[158:161], v[24:27]
	v_mfma_f32_16x16x32_bf16 v[16:19], v[230:233], v[190:193], v[16:19]
	v_mfma_f32_16x16x32_bf16 v[8:11], v[238:241], v[190:193], v[8:11]
	v_mfma_f32_16x16x32_bf16 v[4:7], v[230:233], v[198:201], v[4:7]
	v_mfma_f32_16x16x32_bf16 v[0:3], v[238:241], v[198:201], v[0:3]
	s_barrier
	s_cbranch_scc1 .LBB0_119

; template <class Epi>
; __device__ __forceinline__ void gemm_phase(LAS unsigned char* lds, const Gemm g, const StaticOrder& S, const Epi& E) {
;     ...
;         }
;         E(acc, cur, wr, wc, fr, fq, rsl + (ui & 1) * 256);
;         if (!has_next) break;
.LBB0_119:
	s_waitcnt lgkmcnt(0)
	s_cmpk_gt_u32 s79, 0xff
	s_cbranch_scc1 .Lresync_x
	s_barrier
